# stack1 + work rebalancing: leading waves issue all 16 V-tile DMA pieces, lagging waves only K pieces
# baseline (speedup 1.0000x reference)
.LBB0_717:
	s_add_i32 s53, s55, 1
	s_mov_b32 s52, s47
	s_mov_b32 s47, s54
	s_and_b64 vcc, exec, s[4:5]
	s_cbranch_vccnz .Lattn_lag
	s_cmp_ge_u32 s53, s43
	s_cbranch_scc1 .LBB0_724
	s_bitcmp1_b32 s53, 0
	s_cselect_b32 s54, 0x6000, 0
	s_add_i32 s54, s54, 0
	v_lshl_add_u64 v[130:131], v[180:181], 0, v[166:167]
	s_add_i32 m0, s54, s23
	s_nop 0
	global_load_lds_dwordx4 v[130:131], off
	v_lshl_add_u64 v[130:131], v[178:179], 0, v[166:167]
	s_add_i32 m0, s54, s24
	s_nop 0
	global_load_lds_dwordx4 v[130:131], off
	s_add_i32 m0, s54, s25
	s_lshl_b32 s54, s44, 14
	s_add_i32 s54, s54, 0
	v_lshl_add_u64 v[130:131], v[176:177], 0, v[166:167]
	s_add_i32 s56, s54, s23
	global_load_lds_dwordx4 v[130:131], off
	s_and_b64 vcc, exec, s[6:7]
	s_cbranch_vccz .Lattn_lead_nov
	v_lshl_add_u64 v[130:131], v[182:183], 0, v[166:167]
	s_add_i32 m0, s56, 0xc000
	s_add_i32 s54, s54, s24
	global_load_lds_dwordx4 v[130:131], off
	v_lshl_add_u64 v[130:131], v[184:185], 0, v[166:167]
	s_add_i32 m0, s54, 0xc000
	s_nop 0
	global_load_lds_dwordx4 v[130:131], off
	s_mov_b64 s[76:77], 0x200000
	v_lshl_add_u64 v[130:131], v[182:183], 0, v[166:167]
	v_lshl_add_u64 v[130:131], v[130:131], 0, s[76:77]
	s_add_i32 m0, s56, 0xd000
	s_nop 0
	global_load_lds_dwordx4 v[130:131], off
	v_lshl_add_u64 v[130:131], v[184:185], 0, v[166:167]
	v_lshl_add_u64 v[130:131], v[130:131], 0, s[76:77]
	s_add_i32 m0, s54, 0xd000
	s_nop 0
	global_load_lds_dwordx4 v[130:131], off
.Lattn_lead_nov:
	s_andn2_b64 vcc, exec, s[4:5]
	s_cbranch_vccz .LBB0_725

.Lattn_lag:
	v_lshl_add_u32 v0, s52, 14, v234
	ds_read_b128 v[130:133], v0 offset:49152
	ds_read_b128 v[134:137], v0 offset:50176
	ds_read_b128 v[138:141], v0 offset:51200
	ds_read_b128 v[142:145], v0 offset:52224
	s_waitcnt lgkmcnt(3)
	v_mfma_f32_16x16x32_bf16 v[110:113], v[130:133], v[114:117], v[110:113]
	v_mfma_f32_16x16x32_bf16 v[30:33], v[130:133], v[122:125], v[30:33]
	s_waitcnt lgkmcnt(2)
	v_mfma_f32_16x16x32_bf16 v[110:113], v[134:137], v[118:121], v[110:113]
	v_mfma_f32_16x16x32_bf16 v[30:33], v[134:137], v[126:129], v[30:33]
	ds_read_b128 v[130:133], v0 offset:53248
	ds_read_b128 v[134:137], v0 offset:54272
	s_waitcnt lgkmcnt(2)
	v_mfma_f32_16x16x32_bf16 v[106:109], v[138:141], v[114:117], v[106:109]
	v_mfma_f32_16x16x32_bf16 v[26:29], v[138:141], v[122:125], v[26:29]
	v_mfma_f32_16x16x32_bf16 v[106:109], v[142:145], v[118:121], v[106:109]
	v_mfma_f32_16x16x32_bf16 v[26:29], v[142:145], v[126:129], v[26:29]
	ds_read_b128 v[138:141], v0 offset:55296
	ds_read_b128 v[142:145], v0 offset:56320
	s_waitcnt lgkmcnt(2)
	v_mfma_f32_16x16x32_bf16 v[102:105], v[130:133], v[114:117], v[102:105]
	v_mfma_f32_16x16x32_bf16 v[22:25], v[130:133], v[122:125], v[22:25]
	v_mfma_f32_16x16x32_bf16 v[102:105], v[134:137], v[118:121], v[102:105]
	v_mfma_f32_16x16x32_bf16 v[22:25], v[134:137], v[126:129], v[22:25]
	ds_read_b128 v[130:133], v0 offset:57344
	ds_read_b128 v[134:137], v0 offset:58368
	s_waitcnt lgkmcnt(2)
	v_mfma_f32_16x16x32_bf16 v[98:101], v[138:141], v[114:117], v[98:101]
	v_mfma_f32_16x16x32_bf16 v[18:21], v[138:141], v[122:125], v[18:21]
	v_mfma_f32_16x16x32_bf16 v[98:101], v[142:145], v[118:121], v[98:101]
	v_mfma_f32_16x16x32_bf16 v[18:21], v[142:145], v[126:129], v[18:21]
	ds_read_b128 v[138:141], v0 offset:59392
	ds_read_b128 v[142:145], v0 offset:60416
	s_waitcnt lgkmcnt(2)
	v_mfma_f32_16x16x32_bf16 v[90:93], v[130:133], v[114:117], v[90:93]
	v_mfma_f32_16x16x32_bf16 v[14:17], v[130:133], v[122:125], v[14:17]
	v_mfma_f32_16x16x32_bf16 v[90:93], v[134:137], v[118:121], v[90:93]
	v_mfma_f32_16x16x32_bf16 v[14:17], v[134:137], v[126:129], v[14:17]
	ds_read_b128 v[130:133], v0 offset:61440
	ds_read_b128 v[134:137], v0 offset:62464
	s_waitcnt lgkmcnt(2)
	v_mfma_f32_16x16x32_bf16 v[70:73], v[138:141], v[114:117], v[70:73]
	v_mfma_f32_16x16x32_bf16 v[10:13], v[138:141], v[122:125], v[10:13]
	v_mfma_f32_16x16x32_bf16 v[70:73], v[142:145], v[118:121], v[70:73]
	v_mfma_f32_16x16x32_bf16 v[10:13], v[142:145], v[126:129], v[10:13]
	ds_read_b128 v[138:141], v0 offset:63488
	ds_read_b128 v[142:145], v0 offset:64512
	s_waitcnt lgkmcnt(2)
	v_mfma_f32_16x16x32_bf16 v[38:41], v[130:133], v[114:117], v[38:41]
	v_mfma_f32_16x16x32_bf16 v[6:9], v[130:133], v[122:125], v[6:9]
	v_mfma_f32_16x16x32_bf16 v[38:41], v[134:137], v[118:121], v[38:41]
	v_mfma_f32_16x16x32_bf16 v[6:9], v[134:137], v[126:129], v[6:9]
	s_waitcnt lgkmcnt(0)
	v_mfma_f32_16x16x32_bf16 v[34:37], v[138:141], v[114:117], v[34:37]
	v_mfma_f32_16x16x32_bf16 v[2:5], v[138:141], v[122:125], v[2:5]
	v_mfma_f32_16x16x32_bf16 v[34:37], v[142:145], v[118:121], v[34:37]
	v_mfma_f32_16x16x32_bf16 v[2:5], v[142:145], v[126:129], v[2:5]
	s_cmp_ge_u32 s53, s43
	s_cbranch_scc1 .Lattn_lag_nodma
	s_bitcmp1_b32 s53, 0
	s_cselect_b32 s54, 0x6000, 0
	s_add_i32 s54, s54, 0
	v_lshl_add_u64 v[130:131], v[180:181], 0, v[166:167]
	s_add_i32 m0, s54, s23
	s_nop 0
	global_load_lds_dwordx4 v[130:131], off
	v_lshl_add_u64 v[130:131], v[178:179], 0, v[166:167]
	s_add_i32 m0, s54, s24
	s_nop 0
	global_load_lds_dwordx4 v[130:131], off
	s_add_i32 m0, s54, s25
	s_lshl_b32 s54, s44, 14
	s_add_i32 s54, s54, 0
	v_lshl_add_u64 v[130:131], v[176:177], 0, v[166:167]
	s_add_i32 s56, s54, s23
	global_load_lds_dwordx4 v[130:131], off
.Lattn_lag_nodma:
	s_lshl_b32 s4, s47, 14
	s_add_i32 s54, s4, 0
	s_cmp_gt_i32 s42, s45
	s_cbranch_scc0 .LBB0_720
	s_branch .LBB0_726
